# scan stage Y: all operand reads up front, P3/P1 MFMAs directly behind the state-update MFMAs (no hazard nops, no exposed LDS wait for the Gram operands)
# baseline (speedup 1.0000x reference)
.Lpq0_end:
	s_waitcnt lgkmcnt(0)
	s_barrier
	v_add_u32_e32 v200, v146, v145
	v_add_u32_e32 v112, v156, v163
	ds_read_b128 v[48:51], v180
	ds_read_b128 v[52:55], v112 offset:62976
	ds_read_b128 v[56:59], v112 offset:64256
	v_sub_u32_e32 v113, v164, v143
	v_mad_u32_u24 v113, v145, 5, v113
	v_add_u32_e32 v113, 0x18d00, v113
	ds_read_b128 v[88:91], v113
	ds_read_b128 v[92:95], v113 offset:64
	s_and_saveexec_b64 s[2:3], s[56:57]
	s_cbranch_execz .Lsy0_r1
	ds_read_b128 v[62:65], v175
	ds_read_b128 v[66:69], v200

.Lsy0_r2:
	s_or_b64 exec, exec, s[2:3]
	s_and_b64 s[98:99], s[56:57], exec
	s_cbranch_scc0 .Lcp0
	s_cmp_gt_u32 s36, 62
	s_cbranch_scc1 .Lcp0
	s_cmp_eq_u32 s36, 0
	s_cbranch_scc1 .Lvw0
	s_waitcnt vmcnt(14)
	s_branch .Lvx0

.Lcp0:
	v_mul_u32_u24_e32 v114, 5, v145
	v_sub_u32_e32 v114, v143, v114
	v_mul_i32_i24_e32 v114, 0x47, v114
	v_ashrrev_i32_e32 v114, 1, v114
	v_add_u32_e32 v114, v181, v114
	s_waitcnt lgkmcnt(2)
	v_mfma_f32_16x16x32_bf16 v[14:17], v[52:55], v[48:51], v[14:17]
	v_mfma_f32_16x16x32_bf16 v[18:21], v[56:59], v[48:51], v[18:21]
	s_and_saveexec_b64 s[2:3], s[56:57]
	s_cbranch_execz .Lsy0_m1
	s_waitcnt lgkmcnt(0)
	v_mfma_f32_16x16x32_bf16 v[22:25], v[62:65], v[66:69], v[22:25]
.Lsy0_m1:
	s_or_b64 exec, exec, s[2:3]
	s_and_saveexec_b64 s[2:3], s[46:47]
	s_cbranch_execz .Lsy0_m2
	v_mfma_f32_16x16x32_bf16 v[22:25], v[70:73], v[74:77], 0
	s_waitcnt lgkmcnt(0)
	v_mfma_f32_16x16x32_bf16 v[22:25], v[78:81], v[82:85], v[22:25]
.Lsy0_m2:
	s_or_b64 exec, exec, s[2:3]
	s_waitcnt lgkmcnt(0)
	s_nop 3
	v_pk_mul_f32 v[14:15], v[14:15], v[88:89]
	v_pk_mul_f32 v[16:17], v[16:17], v[90:91]
	v_pk_mul_f32 v[18:19], v[18:19], v[92:93]
	v_pk_mul_f32 v[20:21], v[20:21], v[94:95]
	v_cvt_pk_bf16_f32 v116, v14, v15
	v_cvt_pk_bf16_f32 v117, v16, v17
	v_cvt_pk_bf16_f32 v118, v18, v19
	v_cvt_pk_bf16_f32 v119, v20, v21
	ds_write_b64 v114, v[116:117]
	ds_write_b64 v114, v[118:119] offset:32
	s_nop 3
	s_and_saveexec_b64 s[2:3], s[56:57]
	s_cbranch_execz .Lsy0_w1
	ds_write_b128 v179, v[22:25]

.Lpq1_end:
	s_waitcnt lgkmcnt(0)
	s_barrier
	s_and_b64 s[24:25], s[46:47], s[2:3]
	ds_read_b128 v[48:51], v180 offset:5120
	ds_read_b128 v[52:55], v170 offset:5120
	ds_read_b128 v[56:59], v170 offset:6400
	v_sub_u32_e32 v113, v164, v143
	v_mad_u32_u24 v113, v145, 5, v113
	v_add_u32_e32 v113, 0x18e00, v113
	ds_read_b128 v[88:91], v113
	ds_read_b128 v[92:95], v113 offset:64
	s_and_saveexec_b64 s[74:75], s[56:57]
	s_cbranch_execz .Lsy1_r1
	ds_read_b128 v[62:65], v175 offset:5120
	ds_read_b128 v[66:69], v200 offset:1280

.Lsy1_r2:
	s_or_b64 exec, exec, s[74:75]
	s_and_b64 s[98:99], s[56:57], exec
	s_cbranch_scc0 .Lcp1
	s_cmp_gt_u32 s36, 62
	s_cbranch_scc1 .Lcp1
	s_cmp_eq_u32 s36, 0
	s_cbranch_scc1 .Lvw1
	s_cmp_gt_u32 s36, 61
	s_cbranch_scc1 .Lvw1
	s_waitcnt vmcnt(14)
	s_branch .Lvx1

.Lcp1:
	v_mul_u32_u24_e32 v114, 5, v145
	v_sub_u32_e32 v114, v143, v114
	v_mul_i32_i24_e32 v114, 0x47, v114
	v_ashrrev_i32_e32 v114, 1, v114
	v_add_u32_e32 v114, v181, v114
	s_waitcnt lgkmcnt(2)
	v_mfma_f32_16x16x32_bf16 v[14:17], v[52:55], v[48:51], v[14:17]
	v_mfma_f32_16x16x32_bf16 v[18:21], v[56:59], v[48:51], v[18:21]
	s_and_saveexec_b64 s[74:75], s[56:57]
	s_cbranch_execz .Lsy1_m1
	s_waitcnt lgkmcnt(0)
	v_mfma_f32_16x16x32_bf16 v[22:25], v[62:65], v[66:69], v[22:25]
.Lsy1_m1:
	s_or_b64 exec, exec, s[74:75]
	s_and_saveexec_b64 s[74:75], s[24:25]
	s_cbranch_execz .Lsy1_m2
	v_mfma_f32_16x16x32_bf16 v[22:25], v[70:73], v[74:77], 0
	s_waitcnt lgkmcnt(0)
	v_mfma_f32_16x16x32_bf16 v[22:25], v[78:81], v[82:85], v[22:25]
.Lsy1_m2:
	s_or_b64 exec, exec, s[74:75]
	s_waitcnt lgkmcnt(0)
	s_nop 3
	v_pk_mul_f32 v[14:15], v[14:15], v[88:89]
	v_pk_mul_f32 v[16:17], v[16:17], v[90:91]
	v_pk_mul_f32 v[18:19], v[18:19], v[92:93]
	v_pk_mul_f32 v[20:21], v[20:21], v[94:95]
	v_cvt_pk_bf16_f32 v116, v14, v15
	v_cvt_pk_bf16_f32 v117, v16, v17
	v_cvt_pk_bf16_f32 v118, v18, v19
	v_cvt_pk_bf16_f32 v119, v20, v21
	ds_write_b64 v114, v[116:117]
	ds_write_b64 v114, v[118:119] offset:32
	s_nop 3
	s_and_saveexec_b64 s[74:75], s[56:57]
	s_cbranch_execz .Lsy1_w1
	ds_write_b128 v179, v[22:25] offset:4096
